# differential loop role B: staging stores in the middle of its QK phase (after the fourth QK MFMA)
# speedup vs baseline: 1.0069x; 1.0069x over previous
; template <bool DIFF>
; __device__ __forceinline__ void attn_unit(const AttnP& A, int b, int h, int qi, ldsp lds) {
;     ...
;             QK_BLOCK();
;             s16x4 vlo[8], vhi[8];
; #pragma unroll
;             for (int t = 0; t < 2; ++t)
; #pragma unroll
;                 for (int j = 0; j < 4; ++j) { vlo[t * 4 + j] = vtr(Vb + trb + (16 * j) * VP + t * 64); vhi[t * 4 + j] = vtr(Vb + trb + (16 * j + 8) * VP + t * 64); }
;             __builtin_amdgcn_sched_barrier(0);
;             MASK_BLOCK();
;             bool full = (kt == kt0);
;             float psa, psb;
;             if (!full) {
;                 EXPSUM_BLOCK();
;                 if (__any(psa + psb > 1.0e18f)) { full = true; QK_BLOCK();
;     ...
;             bf16x8 pw[4];
; #pragma unroll
;             for (int j = 0; j < 4; ++j) {
;                 u32x4 pk;
;                 if (j < 2) { const int rb = 8 * (j & 1); pk.x = cvtpk(s0[rb], s0[rb + 1]); pk.y = cvtpk(s0[rb + 2], s0[rb + 3]); pk.z = cvtpk(s0[rb + 4], s0[rb + 5]); pk.w = cvtpk(s0[rb + 6], s0[rb + 7]); }
;                 else { const int rb = 8 * (j & 1); pk.x = cvtpk(s1[rb], s1[rb + 1]); pk.y = cvtpk(s1[rb + 2], s1[rb + 3]); pk.z = cvtpk(s1[rb + 4], s1[rb + 5]); pk.w = cvtpk(s1[rb + 6], s1[rb + 7]); }
;                 pw[j] = __builtin_bit_cast(bf16x8, pk);
;             }
;             __builtin_amdgcn_sched_barrier(0);
;             __builtin_amdgcn_s_setprio(1);
; #pragma unroll
;             for (int t = 0; t < 2; ++t)
; #pragma unroll
;                 for (int j = 0; j < 4; ++j) {
;                     const bf16x8 vf = (bf16x8){vlo[t * 4 + j][0], vlo[t * 4 + j][1], vlo[t * 4 + j][2], vlo[t * 4 + j][3], vhi[t * 4 + j][0], vhi[t * 4 + j][1], vhi[t * 4 + j][2], vhi[t * 4 + j][3]};
;                     o[t] = __builtin_amdgcn_mfma_f32_32x32x16_bf16(vf, pw[j], o[t], 0, 0, 0);
;                 }
;             if (DIFF) {
; #pragma unroll
;                 for (int t = 2; t < NTD; ++t)
; #pragma unroll
;                     for (int j = 0; j < 4; ++j) { vlo[(t - 2) * 4 + j] = vtr(Vb + trb + (16 * j) * VP + t * 64); vhi[(t - 2) * 4 + j] = vtr(Vb + trb + (16 * j + 8) * VP + t * 64); }
;                 __builtin_amdgcn_sched_barrier(0);
; #pragma unroll
;                 for (int t = 2; t < NTD; ++t)
; #pragma unroll
;                     for (int j = 0; j < 4; ++j) {
;                         const int i = (t - 2) * 4 + j;
.Ldb_s_even:
	v_exp_f32_e32 v148, v98
	v_exp_f32_e32 v164, v82
	v_exp_f32_e32 v149, v99
	v_exp_f32_e32 v165, v83
	v_add_f32_e32 v237, 0, v148
	v_add_f32_e32 v238, 0, v164
	v_exp_f32_e32 v150, v100
	v_exp_f32_e32 v166, v84
	v_add_f32_e32 v237, v149, v237
	v_add_f32_e32 v238, v165, v238
	v_exp_f32_e32 v151, v101
	v_exp_f32_e32 v167, v85
	v_add_f32_e32 v237, v150, v237
	v_add_f32_e32 v238, v166, v238
	v_exp_f32_e32 v152, v102
	v_exp_f32_e32 v168, v86
	v_add_f32_e32 v237, v151, v237
	v_add_f32_e32 v238, v167, v238
	v_exp_f32_e32 v153, v103
	v_exp_f32_e32 v169, v87
	v_add_f32_e32 v237, v152, v237
	v_add_f32_e32 v238, v168, v238
	v_exp_f32_e32 v154, v104
	v_exp_f32_e32 v170, v88
	v_add_f32_e32 v237, v153, v237
	v_add_f32_e32 v238, v169, v238
	v_exp_f32_e32 v155, v105
	v_exp_f32_e32 v171, v89
	v_add_f32_e32 v237, v154, v237
	v_add_f32_e32 v238, v170, v238
	v_exp_f32_e32 v156, v106
	v_exp_f32_e32 v172, v90
	v_add_f32_e32 v237, v155, v237
	v_add_f32_e32 v238, v171, v238
	v_exp_f32_e32 v157, v107
	v_exp_f32_e32 v173, v91
	v_add_f32_e32 v237, v156, v237
	v_add_f32_e32 v238, v172, v238
	v_exp_f32_e32 v158, v108
	v_exp_f32_e32 v174, v92
	v_add_f32_e32 v237, v157, v237
	v_add_f32_e32 v238, v173, v238
	v_exp_f32_e32 v159, v109
	v_exp_f32_e32 v175, v93
	v_add_f32_e32 v237, v158, v237
	v_add_f32_e32 v238, v174, v238
	v_exp_f32_e32 v160, v110
	v_exp_f32_e32 v176, v94
	v_add_f32_e32 v237, v159, v237
	v_add_f32_e32 v238, v175, v238
	v_exp_f32_e32 v161, v111
	v_exp_f32_e32 v177, v95
	v_add_f32_e32 v237, v160, v237
	v_add_f32_e32 v238, v176, v238
	v_exp_f32_e32 v162, v112
	v_exp_f32_e32 v178, v96
	v_add_f32_e32 v237, v161, v237
	v_add_f32_e32 v238, v177, v238
	v_exp_f32_e32 v163, v113
	v_exp_f32_e32 v179, v97
	v_add_f32_e32 v237, v162, v237
	v_add_f32_e32 v238, v178, v238
	s_nop 0
	v_add_f32_e32 v237, v163, v237
	v_add_f32_e32 v238, v179, v238
	v_add_f32_e32 v204, v237, v238
	v_cmp_lt_f32_e32 vcc, s85, v204
	s_cbranch_vccnz .Ldb_s_slow
	ds_read_b64_tr_b16 v[90:91], v252 offset:17472
	ds_read_b64_tr_b16 v[92:93], v252 offset:20032
	ds_read_b64_tr_b16 v[94:95], v252 offset:17408
	ds_read_b64_tr_b16 v[96:97], v252 offset:19968
	ds_read_b64_tr_b16 v[106:107], v252 offset:22592
	ds_read_b64_tr_b16 v[108:109], v252 offset:25152
	ds_read_b64_tr_b16 v[110:111], v252 offset:22528
	ds_read_b64_tr_b16 v[112:113], v252 offset:25088
	ds_read_b64_tr_b16 v[240:241], v252 offset:27712
	ds_read_b64_tr_b16 v[242:243], v252 offset:30272
	v_cvt_pk_bf16_f32 v98, v148, v149
	v_cvt_pk_bf16_f32 v99, v150, v151
	v_cvt_pk_bf16_f32 v100, v152, v153
	v_cvt_pk_bf16_f32 v101, v154, v155
	v_cvt_pk_bf16_f32 v102, v156, v157
	v_cvt_pk_bf16_f32 v103, v158, v159
	v_cvt_pk_bf16_f32 v104, v160, v161
	v_cvt_pk_bf16_f32 v105, v162, v163
	v_cvt_pk_bf16_f32 v82, v164, v165
	v_cvt_pk_bf16_f32 v83, v166, v167
	v_cvt_pk_bf16_f32 v84, v168, v169
	v_cvt_pk_bf16_f32 v85, v170, v171
	v_cvt_pk_bf16_f32 v86, v172, v173
	v_cvt_pk_bf16_f32 v87, v174, v175
	v_cvt_pk_bf16_f32 v88, v176, v177
	v_cvt_pk_bf16_f32 v89, v178, v179
	v_add_f32_e32 v230, v204, v230
	ds_read_b64_tr_b16 v[148:149], v252 offset:27648
	ds_read_b64_tr_b16 v[150:151], v252 offset:30208
	ds_read_b64_tr_b16 v[152:153], v252 offset:32768
	ds_read_b64_tr_b16 v[154:155], v252 offset:35328
	ds_read_b64_tr_b16 v[156:157], v252 offset:32832
	ds_read_b64_tr_b16 v[158:159], v252 offset:35392
	s_setprio 1
	s_waitcnt lgkmcnt(14)
	v_mfma_f32_32x32x16_bf16 v[34:49], v[90:93], v[98:101], v[34:49]
	ds_read_b64_tr_b16 v[160:161], v252 offset:17536
	ds_read_b64_tr_b16 v[162:163], v252 offset:20096
	s_waitcnt lgkmcnt(14)
	v_mfma_f32_32x32x16_bf16 v[50:65], v[94:97], v[98:101], v[50:65]
	ds_read_b64_tr_b16 v[164:165], v252 offset:17600
	ds_read_b64_tr_b16 v[166:167], v252 offset:20160
	s_waitcnt lgkmcnt(14)
	v_mfma_f32_32x32x16_bf16 v[34:49], v[106:109], v[102:105], v[34:49]
	ds_read_b64_tr_b16 v[168:169], v252 offset:22656
	ds_read_b64_tr_b16 v[170:171], v252 offset:25216
	s_waitcnt lgkmcnt(14)
	v_mfma_f32_32x32x16_bf16 v[50:65], v[110:113], v[102:105], v[50:65]
	ds_read_b64_tr_b16 v[172:173], v252 offset:22720
	ds_read_b64_tr_b16 v[174:175], v252 offset:25280
	s_waitcnt lgkmcnt(14)
	v_mfma_f32_32x32x16_bf16 v[34:49], v[240:243], v[82:85], v[34:49]
	ds_read_b64_tr_b16 v[176:177], v252 offset:27776
	ds_read_b64_tr_b16 v[178:179], v252 offset:30336
	s_waitcnt lgkmcnt(14)
	v_mfma_f32_32x32x16_bf16 v[50:65], v[148:151], v[82:85], v[50:65]
	ds_read_b64_tr_b16 v[90:91], v252 offset:27840
	ds_read_b64_tr_b16 v[92:93], v252 offset:30400
	s_waitcnt lgkmcnt(14)
	v_mfma_f32_32x32x16_bf16 v[50:65], v[152:155], v[86:89], v[50:65]
	ds_read_b64_tr_b16 v[94:95], v252 offset:32896
	ds_read_b64_tr_b16 v[96:97], v252 offset:35456
	s_waitcnt lgkmcnt(14)
	v_mfma_f32_32x32x16_bf16 v[34:49], v[156:159], v[86:89], v[34:49]
	ds_read_b64_tr_b16 v[106:107], v252 offset:32960
	ds_read_b64_tr_b16 v[108:109], v252 offset:35520
	s_waitcnt lgkmcnt(14)
	v_mfma_f32_32x32x16_bf16 v[18:33], v[160:163], v[98:101], v[18:33]
	ds_read_b128 v[240:243], v234
	s_waitcnt lgkmcnt(13)
	v_mfma_f32_32x32x16_bf16 v[2:17], v[164:167], v[98:101], v[2:17]
	ds_read_b128 v[148:151], v234 offset:8704
	s_waitcnt lgkmcnt(12)
	v_mfma_f32_32x32x16_bf16 v[18:33], v[168:171], v[102:105], v[18:33]
	ds_read_b128 v[152:155], v234 offset:32
	s_waitcnt lgkmcnt(11)
	v_mfma_f32_32x32x16_bf16 v[2:17], v[172:175], v[102:105], v[2:17]
	ds_read_b128 v[156:159], v234 offset:8736
	s_waitcnt lgkmcnt(10)
	v_mfma_f32_32x32x16_bf16 v[18:33], v[176:179], v[82:85], v[18:33]
	ds_read_b128 v[160:163], v234 offset:64
	s_waitcnt lgkmcnt(9)
	v_mfma_f32_32x32x16_bf16 v[2:17], v[90:93], v[82:85], v[2:17]
	ds_read_b128 v[164:167], v234 offset:8768
	s_waitcnt lgkmcnt(8)
; __device__ __forceinline__ s16x4 vtr(ldsp p) { return __builtin_bit_cast(s16x4, __builtin_amdgcn_ds_read_tr16_b64_v4i16((LAS v4i16_t*)p)); }
; #define MASK_BLOCK() do { if (kt == 0 || kt >= diag0) { \
;             _Pragma("unroll") for (int r = 0; r < 16; ++r) { const int kpp = 64 * kt + crow(r, hi); \
;                 if (kpp < 48 || kpp > q_pp) s0[r] = -INFINITY; \
;                 if (kpp + 32 < 48 || kpp + 32 > q_pp) s1[r] = -INFINITY; } } } while (0)
; #define EXPSUM_BLOCK() do { psa = 0.f; psb = 0.f; \
;             _Pragma("unroll") for (int r = 0; r < 16; ++r) { s0[r] = __builtin_amdgcn_exp2f(s0[r]); s1[r] = __builtin_amdgcn_exp2f(s1[r]); psa += s0[r]; asm("" : "+v"(psa)); psb += s1[r]; asm("" : "+v"(psb)); } } while (0)
; template <bool DIFF>
; __device__ __forceinline__ void attn_unit(const AttnP& A, int b, int h, int qi, ldsp lds) {
;     ...
;             QK_BLOCK();
;             s16x4 vlo[8], vhi[8];
; #pragma unroll
;             for (int t = 0; t < 2; ++t)
; #pragma unroll
;                 for (int j = 0; j < 4; ++j) { vlo[t * 4 + j] = vtr(Vb + trb + (16 * j) * VP + t * 64); vhi[t * 4 + j] = vtr(Vb + trb + (16 * j + 8) * VP + t * 64); }
;             __builtin_amdgcn_sched_barrier(0);
;             MASK_BLOCK();
;             bool full = (kt == kt0);
;             float psa, psb;
;             if (!full) {
;                 EXPSUM_BLOCK();
;                 if (__any(psa + psb > 1.0e18f)) { full = true; QK_BLOCK();
	v_mfma_f32_32x32x16_bf16 v[18:33], v[94:97], v[86:89], v[18:33]
	ds_read_b128 v[168:171], v234 offset:96
	s_waitcnt lgkmcnt(7)
	v_mfma_f32_32x32x16_bf16 v[2:17], v[106:109], v[86:89], v[2:17]
	ds_read_b128 v[172:175], v234 offset:8800
	s_waitcnt lgkmcnt(7)
	v_mfma_f32_32x32x16_bf16 v[98:113], v[240:243], v[116:119], v[66:81]
	s_waitcnt lgkmcnt(6)
	v_mfma_f32_32x32x16_bf16 v[82:97], v[148:151], v[116:119], v[66:81]
	s_waitcnt lgkmcnt(5)
	v_mfma_f32_32x32x16_bf16 v[98:113], v[152:155], v[120:123], v[98:113]
	s_waitcnt lgkmcnt(4)
	v_mfma_f32_32x32x16_bf16 v[82:97], v[156:159], v[120:123], v[82:97]
	s_waitcnt vmcnt(0)
	ds_write_b128 v226, v[132:135] offset:38144
	ds_write_b128 v228, v[140:143] offset:38144
	ds_write_b128 v227, v[136:139] offset:17408
	ds_write_b128 v229, v[144:147] offset:17408
	global_load_dwordx4 v[136:139], v[196:197], off offset:2048
	global_load_dwordx4 v[144:147], v[198:199], off offset:2048
	v_lshl_add_u64 v[196:197], v[196:197], 0, s[26:27]
	v_lshl_add_u64 v[198:199], v[198:199], 0, s[26:27]
	global_load_dwordx4 v[132:135], v[196:197], off offset:1024
	global_load_dwordx4 v[140:143], v[198:199], off offset:1024
	s_waitcnt lgkmcnt(7)
	v_mfma_f32_32x32x16_bf16 v[98:113], v[160:163], v[124:127], v[98:113]
	s_waitcnt lgkmcnt(6)
	v_mfma_f32_32x32x16_bf16 v[82:97], v[164:167], v[124:127], v[82:97]
	s_waitcnt lgkmcnt(5)
	v_mfma_f32_32x32x16_bf16 v[98:113], v[168:171], v[128:131], v[98:113]
	s_waitcnt lgkmcnt(4)
	v_mfma_f32_32x32x16_bf16 v[82:97], v[172:175], v[128:131], v[82:97]
	s_setprio 0
	s_waitcnt lgkmcnt(0)
	s_barrier
	s_add_i32 s75, s75, 1
	s_add_i32 s74, s74, 64
	s_cmp_gt_i32 s75, s23
	s_cbranch_scc1 .Ldb_gen
.Ldb_s_odd:
	v_exp_f32_e32 v148, v98
	v_exp_f32_e32 v164, v82
	v_exp_f32_e32 v149, v99
	v_exp_f32_e32 v165, v83
	v_add_f32_e32 v237, 0, v148
	v_add_f32_e32 v238, 0, v164
	v_exp_f32_e32 v150, v100
	v_exp_f32_e32 v166, v84
	v_add_f32_e32 v237, v149, v237
	v_add_f32_e32 v238, v165, v238
	v_exp_f32_e32 v151, v101
	v_exp_f32_e32 v167, v85
	v_add_f32_e32 v237, v150, v237
	v_add_f32_e32 v238, v166, v238
	v_exp_f32_e32 v152, v102
	v_exp_f32_e32 v168, v86
	v_add_f32_e32 v237, v151, v237
	v_add_f32_e32 v238, v167, v238
	v_exp_f32_e32 v153, v103
	v_exp_f32_e32 v169, v87
	v_add_f32_e32 v237, v152, v237
	v_add_f32_e32 v238, v168, v238
	v_exp_f32_e32 v154, v104
	v_exp_f32_e32 v170, v88
	v_add_f32_e32 v237, v153, v237
	v_add_f32_e32 v238, v169, v238
	v_exp_f32_e32 v155, v105
	v_exp_f32_e32 v171, v89
	v_add_f32_e32 v237, v154, v237
	v_add_f32_e32 v238, v170, v238
	v_exp_f32_e32 v156, v106
	v_exp_f32_e32 v172, v90
	v_add_f32_e32 v237, v155, v237
	v_add_f32_e32 v238, v171, v238
	v_exp_f32_e32 v157, v107
	v_exp_f32_e32 v173, v91
	v_add_f32_e32 v237, v156, v237
	v_add_f32_e32 v238, v172, v238
	v_exp_f32_e32 v158, v108
	v_exp_f32_e32 v174, v92
	v_add_f32_e32 v237, v157, v237
	v_add_f32_e32 v238, v173, v238
	v_exp_f32_e32 v159, v109
	v_exp_f32_e32 v175, v93
	v_add_f32_e32 v237, v158, v237
	v_add_f32_e32 v238, v174, v238
	v_exp_f32_e32 v160, v110
	v_exp_f32_e32 v176, v94
	v_add_f32_e32 v237, v159, v237
	v_add_f32_e32 v238, v175, v238
	v_exp_f32_e32 v161, v111
	v_exp_f32_e32 v177, v95
	v_add_f32_e32 v237, v160, v237
	v_add_f32_e32 v238, v176, v238
	v_exp_f32_e32 v162, v112
	v_exp_f32_e32 v178, v96
	v_add_f32_e32 v237, v161, v237
	v_add_f32_e32 v238, v177, v238
	v_exp_f32_e32 v163, v113
	v_exp_f32_e32 v179, v97
	v_add_f32_e32 v237, v162, v237
	v_add_f32_e32 v238, v178, v238
	s_nop 0
	v_add_f32_e32 v237, v163, v237
	v_add_f32_e32 v238, v179, v238
	v_add_f32_e32 v204, v237, v238
	v_cmp_lt_f32_e32 vcc, s85, v204
	s_cbranch_vccnz .Ldb_s_slow
; __device__ __forceinline__ unsigned cvtpk(float lo, float hi) { f32x2 v = {lo, hi}; bf16x2_t b = __builtin_convertvector(v, bf16x2_t); return __builtin_bit_cast(unsigned, b); }
; template <bool DIFF>
; __device__ __forceinline__ void attn_unit(const AttnP& A, int b, int h, int qi, ldsp lds) {
;     ...
;             bf16x8 pw[4];
; #pragma unroll
;             for (int j = 0; j < 4; ++j) {
;                 u32x4 pk;
;                 if (j < 2) { const int rb = 8 * (j & 1); pk.x = cvtpk(s0[rb], s0[rb + 1]); pk.y = cvtpk(s0[rb + 2], s0[rb + 3]); pk.z = cvtpk(s0[rb + 4], s0[rb + 5]); pk.w = cvtpk(s0[rb + 6], s0[rb + 7]); }
;                 else { const int rb = 8 * (j & 1); pk.x = cvtpk(s1[rb], s1[rb + 1]); pk.y = cvtpk(s1[rb + 2], s1[rb + 3]); pk.z = cvtpk(s1[rb + 4], s1[rb + 5]); pk.w = cvtpk(s1[rb + 6], s1[rb + 7]); }
;                 pw[j] = __builtin_bit_cast(bf16x8, pk);
;             }
;             __builtin_amdgcn_sched_barrier(0);
;             __builtin_amdgcn_s_setprio(1);
; #pragma unroll
;             for (int t = 0; t < 2; ++t)
; #pragma unroll
;                 for (int j = 0; j < 4; ++j) {
;                     const bf16x8 vf = (bf16x8){vlo[t * 4 + j][0], vlo[t * 4 + j][1], vlo[t * 4 + j][2], vlo[t * 4 + j][3], vhi[t * 4 + j][0], vhi[t * 4 + j][1], vhi[t * 4 + j][2], vhi[t * 4 + j][3]};
;                     o[t] = __builtin_amdgcn_mfma_f32_32x32x16_bf16(vf, pw[j], o[t], 0, 0, 0);
;                 }
;             if (DIFF) {
; #pragma unroll
;                 for (int t = 2; t < NTD; ++t)
; #pragma unroll
;                     for (int j = 0; j < 4; ++j) { vlo[(t - 2) * 4 + j] = vtr(Vb + trb + (16 * j) * VP + t * 64); vhi[(t - 2) * 4 + j] = vtr(Vb + trb + (16 * j + 8) * VP + t * 64); }
;                 __builtin_amdgcn_sched_barrier(0);
; #pragma unroll
;                 for (int t = 2; t < NTD; ++t)
; #pragma unroll
;                     for (int j = 0; j < 4; ++j) {
;                         const int i = (t - 2) * 4 + j;
;                         const bf16x8 vf = (bf16x8){vlo[i][0], vlo[i][1], vlo[i][2], vlo[i][3], vhi[i][0], vhi[i][1], vhi[i][2], vhi[i][3]};
;                         o[t] = __builtin_amdgcn_mfma_f32_32x32x16_bf16(vf, pw[j], o[t], 0, 0, 0);
;                     }
;             }
;             __builtin_amdgcn_s_setprio(0);
;         }
;         if (kt + 1 < nt) STORE_TILE((kt + 1) & 1);
;         __syncthreads();
;     }
	ds_read_b64_tr_b16 v[90:91], v231 offset:17472
	ds_read_b64_tr_b16 v[92:93], v231 offset:20032
	ds_read_b64_tr_b16 v[94:95], v231 offset:17408
	ds_read_b64_tr_b16 v[96:97], v231 offset:19968
	ds_read_b64_tr_b16 v[106:107], v231 offset:22592
	ds_read_b64_tr_b16 v[108:109], v231 offset:25152
	ds_read_b64_tr_b16 v[110:111], v231 offset:22528
	ds_read_b64_tr_b16 v[112:113], v231 offset:25088
	ds_read_b64_tr_b16 v[240:241], v231 offset:27712
	ds_read_b64_tr_b16 v[242:243], v231 offset:30272
	v_cvt_pk_bf16_f32 v98, v148, v149
	v_cvt_pk_bf16_f32 v99, v150, v151
	v_cvt_pk_bf16_f32 v100, v152, v153
	v_cvt_pk_bf16_f32 v101, v154, v155
	v_cvt_pk_bf16_f32 v102, v156, v157
	v_cvt_pk_bf16_f32 v103, v158, v159
	v_cvt_pk_bf16_f32 v104, v160, v161
	v_cvt_pk_bf16_f32 v105, v162, v163
	v_cvt_pk_bf16_f32 v82, v164, v165
	v_cvt_pk_bf16_f32 v83, v166, v167
	v_cvt_pk_bf16_f32 v84, v168, v169
	v_cvt_pk_bf16_f32 v85, v170, v171
	v_cvt_pk_bf16_f32 v86, v172, v173
	v_cvt_pk_bf16_f32 v87, v174, v175
	v_cvt_pk_bf16_f32 v88, v176, v177
	v_cvt_pk_bf16_f32 v89, v178, v179
	v_add_f32_e32 v230, v204, v230
	ds_read_b64_tr_b16 v[148:149], v231 offset:27648
	ds_read_b64_tr_b16 v[150:151], v231 offset:30208
	ds_read_b64_tr_b16 v[152:153], v231 offset:32768
	ds_read_b64_tr_b16 v[154:155], v231 offset:35328
	ds_read_b64_tr_b16 v[156:157], v231 offset:32832
	ds_read_b64_tr_b16 v[158:159], v231 offset:35392
	s_setprio 1
	s_waitcnt lgkmcnt(14)
	v_mfma_f32_32x32x16_bf16 v[34:49], v[90:93], v[98:101], v[34:49]
	ds_read_b64_tr_b16 v[160:161], v231 offset:17536
	ds_read_b64_tr_b16 v[162:163], v231 offset:20096
	s_waitcnt lgkmcnt(14)
	v_mfma_f32_32x32x16_bf16 v[50:65], v[94:97], v[98:101], v[50:65]
	ds_read_b64_tr_b16 v[164:165], v231 offset:17600
	ds_read_b64_tr_b16 v[166:167], v231 offset:20160
	s_waitcnt lgkmcnt(14)
	v_mfma_f32_32x32x16_bf16 v[34:49], v[106:109], v[102:105], v[34:49]
	ds_read_b64_tr_b16 v[168:169], v231 offset:22656
	ds_read_b64_tr_b16 v[170:171], v231 offset:25216
	s_waitcnt lgkmcnt(14)
	v_mfma_f32_32x32x16_bf16 v[50:65], v[110:113], v[102:105], v[50:65]
	ds_read_b64_tr_b16 v[172:173], v231 offset:22720
	ds_read_b64_tr_b16 v[174:175], v231 offset:25280
	s_waitcnt lgkmcnt(14)
	v_mfma_f32_32x32x16_bf16 v[34:49], v[240:243], v[82:85], v[34:49]
	ds_read_b64_tr_b16 v[176:177], v231 offset:27776
	ds_read_b64_tr_b16 v[178:179], v231 offset:30336
	s_waitcnt lgkmcnt(14)
	v_mfma_f32_32x32x16_bf16 v[50:65], v[148:151], v[82:85], v[50:65]
	ds_read_b64_tr_b16 v[90:91], v231 offset:27840
	ds_read_b64_tr_b16 v[92:93], v231 offset:30400
	s_waitcnt lgkmcnt(14)
	v_mfma_f32_32x32x16_bf16 v[50:65], v[152:155], v[86:89], v[50:65]
	ds_read_b64_tr_b16 v[94:95], v231 offset:32896
	ds_read_b64_tr_b16 v[96:97], v231 offset:35456
	s_waitcnt lgkmcnt(14)
	v_mfma_f32_32x32x16_bf16 v[34:49], v[156:159], v[86:89], v[34:49]
	ds_read_b64_tr_b16 v[106:107], v231 offset:32960
	ds_read_b64_tr_b16 v[108:109], v231 offset:35520
	s_waitcnt lgkmcnt(14)
	v_mfma_f32_32x32x16_bf16 v[18:33], v[160:163], v[98:101], v[18:33]
	ds_read_b128 v[240:243], v234 offset:38144
	s_waitcnt lgkmcnt(13)
	v_mfma_f32_32x32x16_bf16 v[2:17], v[164:167], v[98:101], v[2:17]
	ds_read_b128 v[148:151], v234 offset:46848
	s_waitcnt lgkmcnt(12)
	v_mfma_f32_32x32x16_bf16 v[18:33], v[168:171], v[102:105], v[18:33]
	ds_read_b128 v[152:155], v234 offset:38176
	s_waitcnt lgkmcnt(11)
	v_mfma_f32_32x32x16_bf16 v[2:17], v[172:175], v[102:105], v[2:17]
	ds_read_b128 v[156:159], v234 offset:46880
	s_waitcnt lgkmcnt(10)
	v_mfma_f32_32x32x16_bf16 v[18:33], v[176:179], v[82:85], v[18:33]
	ds_read_b128 v[160:163], v234 offset:38208
	s_waitcnt lgkmcnt(9)
	v_mfma_f32_32x32x16_bf16 v[2:17], v[90:93], v[82:85], v[2:17]
	ds_read_b128 v[164:167], v234 offset:46912
	s_waitcnt lgkmcnt(8)
	v_mfma_f32_32x32x16_bf16 v[18:33], v[94:97], v[86:89], v[18:33]
	ds_read_b128 v[168:171], v234 offset:38240
	s_waitcnt lgkmcnt(7)
	v_mfma_f32_32x32x16_bf16 v[2:17], v[106:109], v[86:89], v[2:17]
	ds_read_b128 v[172:175], v234 offset:46944
	s_waitcnt lgkmcnt(7)
	v_mfma_f32_32x32x16_bf16 v[98:113], v[240:243], v[116:119], v[66:81]
	s_waitcnt lgkmcnt(6)
	v_mfma_f32_32x32x16_bf16 v[82:97], v[148:151], v[116:119], v[66:81]
	s_waitcnt lgkmcnt(5)
	v_mfma_f32_32x32x16_bf16 v[98:113], v[152:155], v[120:123], v[98:113]
	s_waitcnt lgkmcnt(4)
	v_mfma_f32_32x32x16_bf16 v[82:97], v[156:159], v[120:123], v[82:97]
	s_waitcnt vmcnt(0)
	ds_write_b128 v226, v[132:135]
	ds_write_b128 v228, v[140:143]
	ds_write_b128 v227, v[136:139] offset:55552
	ds_write_b128 v229, v[144:147] offset:55552
	global_load_dwordx4 v[136:139], v[196:197], off offset:2048
	global_load_dwordx4 v[144:147], v[198:199], off offset:2048
	v_lshl_add_u64 v[196:197], v[196:197], 0, s[26:27]
	v_lshl_add_u64 v[198:199], v[198:199], 0, s[26:27]
	global_load_dwordx4 v[132:135], v[196:197], off offset:1024
	global_load_dwordx4 v[140:143], v[198:199], off offset:1024
	s_waitcnt lgkmcnt(7)
	v_mfma_f32_32x32x16_bf16 v[98:113], v[160:163], v[124:127], v[98:113]
	s_waitcnt lgkmcnt(6)
	v_mfma_f32_32x32x16_bf16 v[82:97], v[164:167], v[124:127], v[82:97]
	s_waitcnt lgkmcnt(5)
	v_mfma_f32_32x32x16_bf16 v[98:113], v[168:171], v[128:131], v[98:113]
	s_waitcnt lgkmcnt(4)
	v_mfma_f32_32x32x16_bf16 v[82:97], v[172:175], v[128:131], v[82:97]
	s_setprio 0
	s_waitcnt lgkmcnt(0)
	s_barrier
	s_add_i32 s75, s75, 1
	s_add_i32 s74, s74, 64
	s_cmp_le_i32 s75, s23
	s_cbranch_scc1 .Ldb_s_even
